# initial cooperative-groups grid sync replaced by a device-memory ready flag (WG0 zeroes barrier words, publishes a 64-bit magic; others poll), flag cleared at kernel end
# speedup vs baseline: 1.0073x; 1.0073x over previous
.LBB0_6:
	v_lshrrev_b32_e32 v1, 20, v0
	v_lshrrev_b32_e32 v0, 10, v0
	s_waitcnt vmcnt(0) lgkmcnt(0)
	v_or_b32_e32 v0, v0, v1
	s_movk_i32 s2, 0x3ff
	v_and_or_b32 v0, v0, s2, v175
	v_cmp_eq_u32_e32 vcc, 0, v0
	s_waitcnt lgkmcnt(0)
	s_barrier
	s_and_saveexec_b64 s[2:3], vcc
	s_cbranch_execz .LBB0_16
	v_readlane_b32 s6, v253, 0
	v_mov_b32_e32 v2, 0x4000
	s_mov_b32 s7, 0x5afec0de
	s_mov_b32 s8, 0x1eedbeef
	s_cmp_lg_u32 s6, 0
	s_cbranch_scc1 .Lrdy_wait
	buffer_wbl2 sc1
	s_waitcnt vmcnt(0)
	v_mov_b32_e32 v4, s7
	v_mov_b32_e32 v5, s8
	global_store_dwordx2 v2, v[4:5], s[88:89] sc0 sc1
	s_waitcnt vmcnt(0)
	s_branch .Lrdy_done
.Lrdy_wait:
	s_mov_b32 s9, 0
.Lrdy_loop:
	global_load_dwordx2 v[4:5], v2, s[88:89] sc0 sc1
	s_waitcnt vmcnt(0)
	v_cmp_eq_u32_e32 vcc, s7, v4
	v_cmp_eq_u32_e64 s[4:5], s8, v5
	s_nop 3
	s_and_b64 vcc, vcc, s[4:5]
	s_cbranch_vccnz .Lrdy_done
	s_sleep 2
	s_add_i32 s9, s9, 1
	s_cmp_lt_u32 s9, 0x20000
	s_cbranch_scc1 .Lrdy_loop
.Lrdy_done:
.LBB0_15:
.LBB0_16:
	s_or_b64 exec, exec, s[2:3]
	s_load_dwordx16 s[68:83], s[0:1], 0x0
	s_load_dwordx16 s[12:27], s[0:1], 0x40
	s_and_b32 s0, s11, 15
	s_mov_b32 s1, 0
	v_cmp_eq_u32_e32 vcc, 0, v175
	s_lshl_b32 s6, s0, 6
	s_waitcnt lgkmcnt(0)
	v_writelane_b32 v253, s12, 1
	s_barrier
	s_nop 0
	v_writelane_b32 v253, s13, 2
	v_writelane_b32 v253, s14, 3
	v_writelane_b32 v253, s15, 4
	v_writelane_b32 v253, s16, 5
	v_writelane_b32 v253, s17, 6
	v_writelane_b32 v253, s18, 7
	v_writelane_b32 v253, s19, 8
	v_writelane_b32 v253, s20, 9
	v_writelane_b32 v253, s21, 10
	v_writelane_b32 v253, s22, 11
	v_writelane_b32 v253, s23, 12
	v_writelane_b32 v253, s24, 13
	v_writelane_b32 v253, s25, 14
	v_writelane_b32 v253, s26, 15
	v_writelane_b32 v253, s27, 16
	s_and_saveexec_b64 s[2:3], vcc
	s_cbranch_execz .LBB0_19
	s_mov_b64 s[4:5], exec
	v_mbcnt_lo_u32_b32 v0, s4, 0
	v_mbcnt_hi_u32_b32 v0, s5, v0
	v_cmp_eq_u32_e32 vcc, 0, v0
	s_and_b64 s[8:9], exec, vcc
	s_mov_b64 exec, s[8:9]
	s_cbranch_execz .LBB0_19
	s_lshl_b32 s7, s6, 2
	s_bcnt1_i32_b64 s4, s[4:5]
	v_mov_b32_e32 v0, s7
	v_mov_b32_e32 v1, s4
	global_atomic_add v0, v1, s[88:89] offset:1024

.LBB0_1225:
	v_readlane_b32 s6, v253, 0
	v_cmp_eq_u32_e32 vcc, 0, v175
	s_nop 3
	s_cmp_lg_u32 s6, 0
	s_cbranch_scc1 .Lrdy_end
	s_and_saveexec_b64 s[2:3], vcc
	s_cbranch_execz .Lrdy_end
	v_mov_b32_e32 v2, 0x4000
	v_mov_b32_e32 v4, 0
	v_mov_b32_e32 v5, 0
	global_store_dwordx2 v2, v[4:5], s[88:89] sc0 sc1
